# grid barrier: waiting workgroups poll the global generation word instead of their XCD generation word (one hop less after the last arrival)
# speedup vs baseline: 1.0069x; 1.0069x over previous
.LBB0_187:
	s_or_b64 exec, exec, s[4:5]
	v_cvt_f32_u32_e32 v4, v2
	s_waitcnt vmcnt(0)
	v_readfirstlane_b32 s4, v3
	v_sub_u32_e32 v3, 0, v2
	v_rcp_iflag_f32_e32 v4, v4
	v_add_u32_e32 v5, s4, v1
	v_mul_f32_e32 v4, 0x4f7ffffe, v4
	v_cvt_u32_f32_e32 v4, v4
	v_mul_lo_u32 v1, v3, v4
	v_mul_hi_u32 v1, v4, v1
	v_add_u32_e32 v1, v4, v1
	v_mul_hi_u32 v1, v5, v1
	v_mul_lo_u32 v3, v1, v2
	v_sub_u32_e32 v3, v5, v3
	v_add_u32_e32 v4, 1, v1
	v_cmp_ge_u32_e32 vcc, v3, v2
	s_nop 1
	v_cndmask_b32_e32 v1, v1, v4, vcc
	v_sub_u32_e32 v4, v3, v2
	v_cndmask_b32_e32 v3, v3, v4, vcc
	v_add_u32_e32 v4, 1, v1
	v_cmp_ge_u32_e32 vcc, v3, v2
	v_add_u32_e32 v3, 1, v5
	s_nop 0
	v_cndmask_b32_e32 v1, v1, v4, vcc
	v_mul_lo_u32 v4, v2, v1
	v_add_u32_e32 v2, v4, v2
	v_cmp_ne_u32_e32 vcc, v3, v2
	s_and_saveexec_b64 s[4:5], vcc
	s_xor_b64 s[4:5], exec, s[4:5]
	s_cbranch_execz .LBB0_201
	v_readlane_b32 s6, v252, 58
	v_readlane_b32 s7, v252, 59
	s_waitcnt lgkmcnt(0)
	s_nop 3
	global_load_dword v0, v161, s[6:7] sc1
	s_waitcnt vmcnt(0)
	v_cmp_eq_u32_e32 vcc, v0, v1
	s_and_saveexec_b64 s[6:7], vcc
	s_cbranch_execz .LBB0_200
	s_mov_b32 s28, 1
	s_mov_b64 s[8:9], 0
	s_branch .LBB0_191

.LBB0_195:
	v_readlane_b32 s12, v252, 58
	v_readlane_b32 s13, v252, 59
	s_add_i32 s28, s28, 1
	s_mov_b64 s[14:15], -1
	s_nop 2
	global_load_dword v0, v161, s[12:13] sc1
	s_waitcnt vmcnt(0)
	v_cmp_ne_u32_e32 vcc, v0, v1
	s_orn2_b64 s[12:13], vcc, exec
	s_branch .LBB0_190

.LBB0_378:
	s_or_b64 exec, exec, s[4:5]
	v_cvt_f32_u32_e32 v4, v2
	s_waitcnt vmcnt(0)
	v_readfirstlane_b32 s4, v3
	v_sub_u32_e32 v3, 0, v2
	v_rcp_iflag_f32_e32 v4, v4
	v_add_u32_e32 v5, s4, v1
	v_mul_f32_e32 v4, 0x4f7ffffe, v4
	v_cvt_u32_f32_e32 v4, v4
	v_mul_lo_u32 v1, v3, v4
	v_mul_hi_u32 v1, v4, v1
	v_add_u32_e32 v1, v4, v1
	v_mul_hi_u32 v1, v5, v1
	v_mul_lo_u32 v3, v1, v2
	v_sub_u32_e32 v3, v5, v3
	v_add_u32_e32 v4, 1, v1
	v_cmp_ge_u32_e32 vcc, v3, v2
	s_nop 1
	v_cndmask_b32_e32 v1, v1, v4, vcc
	v_sub_u32_e32 v4, v3, v2
	v_cndmask_b32_e32 v3, v3, v4, vcc
	v_add_u32_e32 v4, 1, v1
	v_cmp_ge_u32_e32 vcc, v3, v2
	v_add_u32_e32 v3, 1, v5
	s_nop 0
	v_cndmask_b32_e32 v1, v1, v4, vcc
	v_mul_lo_u32 v4, v2, v1
	v_add_u32_e32 v2, v4, v2
	v_cmp_ne_u32_e32 vcc, v3, v2
	s_and_saveexec_b64 s[4:5], vcc
	s_xor_b64 s[4:5], exec, s[4:5]
	s_cbranch_execz .LBB0_392
	v_readlane_b32 s6, v252, 58
	v_readlane_b32 s7, v252, 59
	s_waitcnt lgkmcnt(0)
	s_nop 3
	global_load_dword v0, v161, s[6:7] sc1
	s_waitcnt vmcnt(0)
	v_cmp_eq_u32_e32 vcc, v0, v1
	s_and_saveexec_b64 s[6:7], vcc
	s_cbranch_execz .LBB0_391
	s_mov_b32 s19, 1
	s_mov_b64 s[8:9], 0
	s_branch .LBB0_382

.LBB0_386:
	v_readlane_b32 s12, v252, 58
	v_readlane_b32 s13, v252, 59
	s_add_i32 s19, s19, 1
	s_mov_b64 s[14:15], -1
	s_nop 2
	global_load_dword v0, v161, s[12:13] sc1
	s_waitcnt vmcnt(0)
	v_cmp_ne_u32_e32 vcc, v0, v1
	s_orn2_b64 s[12:13], vcc, exec
	s_branch .LBB0_381

.LBB0_1340:
	s_or_b64 exec, exec, s[4:5]
	v_cvt_f32_u32_e32 v4, v2
	s_waitcnt vmcnt(0)
	v_readfirstlane_b32 s4, v3
	v_sub_u32_e32 v3, 0, v2
	v_rcp_iflag_f32_e32 v4, v4
	v_add_u32_e32 v5, s4, v1
	v_mul_f32_e32 v4, 0x4f7ffffe, v4
	v_cvt_u32_f32_e32 v4, v4
	v_mul_lo_u32 v1, v3, v4
	v_mul_hi_u32 v1, v4, v1
	v_add_u32_e32 v1, v4, v1
	v_mul_hi_u32 v1, v5, v1
	v_mul_lo_u32 v3, v1, v2
	v_sub_u32_e32 v3, v5, v3
	v_add_u32_e32 v4, 1, v1
	v_cmp_ge_u32_e32 vcc, v3, v2
	s_nop 1
	v_cndmask_b32_e32 v1, v1, v4, vcc
	v_sub_u32_e32 v4, v3, v2
	v_cndmask_b32_e32 v3, v3, v4, vcc
	v_add_u32_e32 v4, 1, v1
	v_cmp_ge_u32_e32 vcc, v3, v2
	v_add_u32_e32 v3, 1, v5
	s_nop 0
	v_cndmask_b32_e32 v1, v1, v4, vcc
	v_mul_lo_u32 v4, v2, v1
	v_add_u32_e32 v2, v4, v2
	v_cmp_ne_u32_e32 vcc, v3, v2
	s_and_saveexec_b64 s[4:5], vcc
	s_xor_b64 s[4:5], exec, s[4:5]
	s_cbranch_execz .LBB0_1354
	v_readlane_b32 s8, v252, 58
	v_readlane_b32 s9, v252, 59
	s_waitcnt lgkmcnt(0)
	s_nop 3
	global_load_dword v0, v161, s[8:9] sc1
	s_waitcnt vmcnt(0)
	v_cmp_eq_u32_e32 vcc, v0, v1
	s_and_saveexec_b64 s[8:9], vcc
	s_cbranch_execz .LBB0_1353
	s_mov_b32 s26, 1
	s_mov_b64 s[10:11], 0
	s_branch .LBB0_1344

.LBB0_1348:
	v_readlane_b32 s14, v252, 58
	v_readlane_b32 s15, v252, 59
	s_add_i32 s26, s26, 1
	s_mov_b64 s[16:17], -1
	s_nop 2
	global_load_dword v0, v161, s[14:15] sc1
	s_waitcnt vmcnt(0)
	v_cmp_ne_u32_e32 vcc, v0, v1
	s_orn2_b64 s[14:15], vcc, exec
	s_branch .LBB0_1343

.LBB0_1644:
	s_or_b64 exec, exec, s[4:5]
	v_cvt_f32_u32_e32 v4, v2
	s_waitcnt vmcnt(0)
	v_readfirstlane_b32 s4, v3
	v_sub_u32_e32 v3, 0, v2
	v_rcp_iflag_f32_e32 v4, v4
	v_add_u32_e32 v5, s4, v1
	v_mul_f32_e32 v4, 0x4f7ffffe, v4
	v_cvt_u32_f32_e32 v4, v4
	v_mul_lo_u32 v1, v3, v4
	v_mul_hi_u32 v1, v4, v1
	v_add_u32_e32 v1, v4, v1
	v_mul_hi_u32 v1, v5, v1
	v_mul_lo_u32 v3, v1, v2
	v_sub_u32_e32 v3, v5, v3
	v_add_u32_e32 v4, 1, v1
	v_cmp_ge_u32_e32 vcc, v3, v2
	s_nop 1
	v_cndmask_b32_e32 v1, v1, v4, vcc
	v_sub_u32_e32 v4, v3, v2
	v_cndmask_b32_e32 v3, v3, v4, vcc
	v_add_u32_e32 v4, 1, v1
	v_cmp_ge_u32_e32 vcc, v3, v2
	v_add_u32_e32 v3, 1, v5
	s_nop 0
	v_cndmask_b32_e32 v1, v1, v4, vcc
	v_mul_lo_u32 v4, v2, v1
	v_add_u32_e32 v2, v4, v2
	v_cmp_ne_u32_e32 vcc, v3, v2
	s_and_saveexec_b64 s[4:5], vcc
	s_xor_b64 s[4:5], exec, s[4:5]
	s_cbranch_execz .LBB0_1658
	v_readlane_b32 s6, v252, 58
	v_readlane_b32 s7, v252, 59
	s_waitcnt lgkmcnt(0)
	s_nop 3
	global_load_dword v0, v161, s[6:7] sc1
	s_waitcnt vmcnt(0)
	v_cmp_eq_u32_e32 vcc, v0, v1
	s_and_saveexec_b64 s[6:7], vcc
	s_cbranch_execz .LBB0_1657
	s_mov_b32 s18, 1
	s_mov_b64 s[8:9], 0
	s_branch .LBB0_1648

.LBB0_1652:
	v_readlane_b32 s12, v252, 58
	v_readlane_b32 s13, v252, 59
	s_add_i32 s18, s18, 1
	s_mov_b64 s[14:15], -1
	s_nop 2
	global_load_dword v0, v161, s[12:13] sc1
	s_waitcnt vmcnt(0)
	v_cmp_ne_u32_e32 vcc, v0, v1
	s_orn2_b64 s[12:13], vcc, exec
	s_branch .LBB0_1647
